# first grid barrier: the sixteen slot-counter loads of the poll loop issued together with one wait instead of one round trip each
# speedup vs baseline: 1.0052x; 1.0052x over previous
; __device__ __forceinline__ unsigned xb_ld(unsigned* p)              { return __hip_atomic_load(p, __ATOMIC_RELAXED, __HIP_MEMORY_SCOPE_AGENT); }
; __device__ __forceinline__ void xcd_barrier_complete(unsigned* bar, unsigned x, unsigned& nloc, unsigned& nx) {
;     const unsigned G = gridDim.x * gridDim.y * gridDim.z;
;     unsigned sum, cnt, mine, sp = 0u;
;     for (;;) {
;         sum = 0u; cnt = 0u; mine = 0u;
; #pragma unroll
;         for (unsigned j = 0; j < 16; ++j) { const unsigned c = xb_ld(&bar[XB_XCNT(j)]); sum += c; cnt += (c > 0u) ? 1u : 0u; mine = (j == x) ? c : mine; }
;         if (sum == G) break;
;         __builtin_amdgcn_s_sleep(1);
;         if ((++sp & 255u) == 0u) { if (xb_ld(&bar[XB_TMO])) break; if (sp > XB_SPIN_CAP) { atomicAdd(&bar[XB_TMO], 1u); break; } }
;     }
;     nloc = mine > 0u ? mine : 1u; nx = cnt > 0u ? cnt : 1u;
; }
.LBB0_751:
	v_readlane_b32 s6, v253, 63
	v_readlane_b32 s7, v254, 0
	s_mov_b64 s[8:9], -1
	s_waitcnt lgkmcnt(0)
	s_nop 2
	global_load_dword v0, v161, s[6:7] sc1
	v_readlane_b32 s6, v254, 1
	v_readlane_b32 s7, v254, 2
	s_nop 4
	global_load_dword v1, v161, s[6:7] sc1
	v_readlane_b32 s6, v254, 3
	v_readlane_b32 s7, v254, 4
	s_nop 4
	global_load_dword v2, v161, s[6:7] sc1
	v_readlane_b32 s6, v254, 5
	v_readlane_b32 s7, v254, 6
	s_nop 4
	global_load_dword v3, v161, s[6:7] sc1
	v_readlane_b32 s6, v254, 7
	v_readlane_b32 s7, v254, 8
	s_nop 4
	global_load_dword v4, v161, s[6:7] sc1
	v_readlane_b32 s6, v254, 9
	v_readlane_b32 s7, v254, 10
	s_nop 4
	global_load_dword v5, v161, s[6:7] sc1
	v_readlane_b32 s6, v254, 11
	v_readlane_b32 s7, v254, 12
	s_nop 4
	global_load_dword v6, v161, s[6:7] sc1
	v_readlane_b32 s6, v254, 13
	v_readlane_b32 s7, v254, 14
	s_nop 4
	global_load_dword v7, v161, s[6:7] sc1
	v_readlane_b32 s6, v254, 15
	v_readlane_b32 s7, v254, 16
	s_nop 4
	global_load_dword v8, v161, s[6:7] sc1
	v_readlane_b32 s6, v254, 17
	v_readlane_b32 s7, v254, 18
	s_nop 4
	global_load_dword v9, v161, s[6:7] sc1
	v_readlane_b32 s6, v254, 19
	v_readlane_b32 s7, v254, 20
	s_nop 4
	global_load_dword v10, v161, s[6:7] sc1
	v_readlane_b32 s6, v254, 21
	v_readlane_b32 s7, v254, 22
	s_nop 4
	global_load_dword v11, v161, s[6:7] sc1
	v_readlane_b32 s6, v254, 23
	v_readlane_b32 s7, v254, 24
	s_nop 4
	global_load_dword v12, v161, s[6:7] sc1
	v_readlane_b32 s6, v254, 25
	v_readlane_b32 s7, v254, 26
	s_nop 4
	global_load_dword v13, v161, s[6:7] sc1
	v_readlane_b32 s6, v254, 27
	v_readlane_b32 s7, v254, 28
	s_nop 4
	global_load_dword v14, v161, s[6:7] sc1
	v_readlane_b32 s6, v254, 29
	v_readlane_b32 s7, v254, 30
	s_nop 4
	global_load_dword v15, v161, s[6:7] sc1
	s_mov_b64 s[6:7], -1
	s_waitcnt vmcnt(0)
	v_add_u32_e32 v16, v1, v0
	v_add_u32_e32 v16, v16, v2
	v_add_u32_e32 v16, v16, v3
	v_add_u32_e32 v16, v16, v4
	v_add_u32_e32 v16, v16, v5
	v_add_u32_e32 v16, v16, v6
	v_add_u32_e32 v16, v16, v7
	v_add_u32_e32 v16, v16, v8
	v_add_u32_e32 v16, v16, v9
	v_add_u32_e32 v16, v16, v10
	v_add_u32_e32 v16, v16, v11
	v_add_u32_e32 v16, v16, v12
	v_add_u32_e32 v16, v16, v13
	v_add_u32_e32 v16, v16, v14
	v_add_u32_e32 v16, v16, v15
	v_cmp_eq_u32_e32 vcc, s35, v16
	s_cbranch_vccnz .LBB0_750
	s_and_b32 s6, s12, 0xff
	s_cmp_eq_u32 s6, 0
	s_mov_b64 s[6:7], -1
	s_mov_b64 s[10:11], -1
	s_sleep 1
	s_cbranch_scc1 .LBB0_755
	s_and_b64 vcc, exec, s[10:11]
	s_cbranch_vccz .LBB0_750
